# P0 w_in transpose: all 32 row loads of an item in flight together (2-iteration load loop unrolled, counted waits)
# speedup vs baseline: 1.0017x; 1.0001x over previous
; #define LAS __attribute__((address_space(3)))
; __device__ __forceinline__ void transpose_item(const float* W, int K, int N, bf16_t* WT, int drow0, LAS float* scr, int k0, int n0, int lane) {
; #pragma unroll 8
;     for (int i = 0; i < 32; ++i) { const int kk = 2 * i + (lane >> 5); scr[kk * 33 + (lane & 31)] = W[(size_t)(k0 + kk) * N + n0 + (lane & 31)]; }
.LBB0_22:
	s_lshl_b32 s12, s9, 1
	s_lshl_b32 s13, s8, 1
	v_or_b32_e32 v48, s12, v1
	v_or_b32_e32 v49, s13, v0
	s_add_i32 s14, s12, 4
	s_add_i32 s15, s13, 4
	s_add_i32 s16, s12, 8
	s_add_i32 s17, s13, 8
	s_add_i32 s18, s12, 12
	s_add_i32 s19, s13, 12
	s_add_i32 s20, s12, 16
	s_add_i32 s21, s13, 16
	s_add_i32 s22, s12, 20
	s_add_i32 s23, s13, 20
	s_add_i32 s24, s12, 24
	s_add_i32 s25, s13, 24
	s_add_i32 s12, s12, 28
	s_add_i32 s13, s13, 28
	v_add_u32_e32 v16, s0, v49
	v_or_b32_e32 v50, s14, v1
	v_or_b32_e32 v51, s15, v0
	v_or_b32_e32 v52, s16, v1
	v_or_b32_e32 v53, s17, v0
	v_or_b32_e32 v54, s18, v1
	v_or_b32_e32 v55, s19, v0
	v_or_b32_e32 v56, s20, v1
	v_or_b32_e32 v57, s21, v0
	v_or_b32_e32 v58, s22, v1
	v_or_b32_e32 v59, s23, v0
	v_or_b32_e32 v60, s24, v1
	v_or_b32_e32 v61, s25, v0
	v_or_b32_e32 v62, s12, v1
	v_or_b32_e32 v63, s13, v0
	v_add_u32_e32 v18, s3, v48
	v_mad_i64_i32 v[16:17], s[12:13], v16, s6, v[8:9]
	v_add_u32_e32 v22, s3, v50
	v_add_u32_e32 v20, s0, v51
	v_add_u32_e32 v26, s3, v52
	v_add_u32_e32 v24, s0, v53
	v_add_u32_e32 v30, s3, v54
	v_add_u32_e32 v28, s0, v55
	v_add_u32_e32 v34, s3, v56
	v_add_u32_e32 v32, s0, v57
	v_add_u32_e32 v38, s3, v58
	v_add_u32_e32 v36, s0, v59
	v_add_u32_e32 v42, s3, v60
	v_add_u32_e32 v40, s0, v61
	v_add_u32_e32 v46, s3, v62
	v_add_u32_e32 v44, s0, v63
	v_mad_i64_i32 v[18:19], s[12:13], v18, s6, v[8:9]
	v_mad_i64_i32 v[20:21], s[12:13], v20, s6, v[8:9]
	v_mad_i64_i32 v[22:23], s[12:13], v22, s6, v[8:9]
	v_mad_i64_i32 v[24:25], s[12:13], v24, s6, v[8:9]
	v_mad_i64_i32 v[26:27], s[12:13], v26, s6, v[8:9]
	v_mad_i64_i32 v[28:29], s[12:13], v28, s6, v[8:9]
	v_mad_i64_i32 v[30:31], s[12:13], v30, s6, v[8:9]
	v_mad_i64_i32 v[32:33], s[12:13], v32, s6, v[8:9]
	v_mad_i64_i32 v[34:35], s[12:13], v34, s6, v[8:9]
	v_mad_i64_i32 v[36:37], s[12:13], v36, s6, v[8:9]
	v_mad_i64_i32 v[38:39], s[12:13], v38, s6, v[8:9]
	v_mad_i64_i32 v[40:41], s[12:13], v40, s6, v[8:9]
	v_mad_i64_i32 v[42:43], s[12:13], v42, s6, v[8:9]
	v_mad_i64_i32 v[44:45], s[12:13], v44, s6, v[8:9]
	v_mad_i64_i32 v[46:47], s[12:13], v46, s6, v[8:9]
	global_load_dword v64, v[16:17], off
	global_load_dword v65, v[18:19], off
	global_load_dword v66, v[20:21], off
	global_load_dword v67, v[22:23], off
	global_load_dword v68, v[24:25], off
	global_load_dword v69, v[26:27], off
	global_load_dword v70, v[28:29], off
	global_load_dword v71, v[30:31], off
	global_load_dword v72, v[32:33], off
	global_load_dword v73, v[34:35], off
	global_load_dword v74, v[36:37], off
	global_load_dword v75, v[38:39], off
	global_load_dword v76, v[40:41], off
	global_load_dword v77, v[42:43], off
	global_load_dword v78, v[44:45], off
	global_load_dword v79, v[46:47], off
	s_add_i32 s8, s8, 16
	s_add_i32 s9, s9, 16
	s_lshl_b32 s12, s9, 1
	s_lshl_b32 s13, s8, 1
	v_or_b32_e32 v112, s12, v1
	v_or_b32_e32 v113, s13, v0
	s_add_i32 s14, s12, 4
	s_add_i32 s15, s13, 4
	s_add_i32 s16, s12, 8
	s_add_i32 s17, s13, 8
	s_add_i32 s18, s12, 12
	s_add_i32 s19, s13, 12
	s_add_i32 s20, s12, 16
	s_add_i32 s21, s13, 16
	s_add_i32 s22, s12, 20
	s_add_i32 s23, s13, 20
	s_add_i32 s24, s12, 24
	s_add_i32 s25, s13, 24
	s_add_i32 s12, s12, 28
	s_add_i32 s13, s13, 28
	v_add_u32_e32 v80, s0, v113
	v_or_b32_e32 v114, s14, v1
	v_or_b32_e32 v115, s15, v0
	v_or_b32_e32 v116, s16, v1
	v_or_b32_e32 v117, s17, v0
	v_or_b32_e32 v118, s18, v1
	v_or_b32_e32 v119, s19, v0
	v_or_b32_e32 v120, s20, v1
	v_or_b32_e32 v121, s21, v0
	v_or_b32_e32 v122, s22, v1
	v_or_b32_e32 v123, s23, v0
	v_or_b32_e32 v124, s24, v1
	v_or_b32_e32 v125, s25, v0
	v_or_b32_e32 v126, s12, v1
	v_or_b32_e32 v127, s13, v0
	v_add_u32_e32 v82, s3, v112
	v_mad_i64_i32 v[80:81], s[12:13], v80, s6, v[8:9]
	v_add_u32_e32 v86, s3, v114
	v_add_u32_e32 v84, s0, v115
	v_add_u32_e32 v90, s3, v116
	v_add_u32_e32 v88, s0, v117
	v_add_u32_e32 v94, s3, v118
	v_add_u32_e32 v92, s0, v119
	v_add_u32_e32 v98, s3, v120
	v_add_u32_e32 v96, s0, v121
	v_add_u32_e32 v102, s3, v122
	v_add_u32_e32 v100, s0, v123
	v_add_u32_e32 v106, s3, v124
	v_add_u32_e32 v104, s0, v125
	v_add_u32_e32 v110, s3, v126
	v_add_u32_e32 v108, s0, v127
	v_mad_i64_i32 v[82:83], s[12:13], v82, s6, v[8:9]
	v_mad_i64_i32 v[84:85], s[12:13], v84, s6, v[8:9]
	v_mad_i64_i32 v[86:87], s[12:13], v86, s6, v[8:9]
	v_mad_i64_i32 v[88:89], s[12:13], v88, s6, v[8:9]
	v_mad_i64_i32 v[90:91], s[12:13], v90, s6, v[8:9]
	v_mad_i64_i32 v[92:93], s[12:13], v92, s6, v[8:9]
	v_mad_i64_i32 v[94:95], s[12:13], v94, s6, v[8:9]
	v_mad_i64_i32 v[96:97], s[12:13], v96, s6, v[8:9]
	v_mad_i64_i32 v[98:99], s[12:13], v98, s6, v[8:9]
	v_mad_i64_i32 v[100:101], s[12:13], v100, s6, v[8:9]
	v_mad_i64_i32 v[102:103], s[12:13], v102, s6, v[8:9]
	v_mad_i64_i32 v[104:105], s[12:13], v104, s6, v[8:9]
	v_mad_i64_i32 v[106:107], s[12:13], v106, s6, v[8:9]
	v_mad_i64_i32 v[108:109], s[12:13], v108, s6, v[8:9]
	v_mad_i64_i32 v[110:111], s[12:13], v110, s6, v[8:9]
	global_load_dword v128, v[80:81], off
	global_load_dword v129, v[82:83], off
	global_load_dword v130, v[84:85], off
	global_load_dword v131, v[86:87], off
	global_load_dword v132, v[88:89], off
	global_load_dword v133, v[90:91], off
	global_load_dword v134, v[92:93], off
	global_load_dword v135, v[94:95], off
	global_load_dword v136, v[96:97], off
	global_load_dword v137, v[98:99], off
	global_load_dword v138, v[100:101], off
	global_load_dword v139, v[102:103], off
	global_load_dword v140, v[104:105], off
	global_load_dword v141, v[106:107], off
	global_load_dword v142, v[108:109], off
	global_load_dword v143, v[110:111], off
	v_mad_u64_u32 v[16:17], s[12:13], v49, s5, v[4:5]
	v_mad_u64_u32 v[18:19], s[12:13], v48, s5, v[4:5]
	v_mad_u64_u32 v[20:21], s[12:13], v51, s5, v[4:5]
	v_mad_u64_u32 v[22:23], s[12:13], v50, s5, v[4:5]
	v_mad_u64_u32 v[24:25], s[12:13], v53, s5, v[4:5]
	v_mad_u64_u32 v[26:27], s[12:13], v52, s5, v[4:5]
	v_mad_u64_u32 v[28:29], s[12:13], v55, s5, v[4:5]
	v_mad_u64_u32 v[30:31], s[12:13], v54, s5, v[4:5]
	v_mad_u64_u32 v[32:33], s[12:13], v57, s5, v[4:5]
	v_mad_u64_u32 v[34:35], s[12:13], v56, s5, v[4:5]
	v_mad_u64_u32 v[36:37], s[12:13], v59, s5, v[4:5]
	v_mad_u64_u32 v[38:39], s[12:13], v58, s5, v[4:5]
	v_mad_u64_u32 v[40:41], s[12:13], v61, s5, v[4:5]
	v_mad_u64_u32 v[42:43], s[12:13], v60, s5, v[4:5]
	v_mad_u64_u32 v[44:45], s[12:13], v63, s5, v[4:5]
	v_mad_u64_u32 v[46:47], s[12:13], v62, s5, v[4:5]
	s_waitcnt vmcnt(31)
; #define LAS __attribute__((address_space(3)))
; __device__ __forceinline__ unsigned pk2(float lo, float hi) { return pk2hw(lo, hi); }
; __device__ __forceinline__ void transpose_item(const float* W, int K, int N, bf16_t* WT, int drow0, LAS float* scr, int k0, int n0, int lane) {
;     ...
;     for (int i = 0; i < 32; ++i) { const int kk = 2 * i + (lane >> 5); scr[kk * 33 + (lane & 31)] = W[(size_t)(k0 + kk) * N + n0 + (lane & 31)]; }
;     asm volatile("s_waitcnt lgkmcnt(0)" ::: "memory");
;     const int c = lane & 7;
; #pragma unroll
;     for (int j = 0; j < 4; ++j) { const int n = (lane >> 3) + 8 * j; const LAS float* s = scr + (8 * c) * 33 + n;
;         u32x4 o; o.x = pk2(s[0 * 33], s[1 * 33]); o.y = pk2(s[2 * 33], s[3 * 33]); o.z = pk2(s[4 * 33], s[5 * 33]); o.w = pk2(s[6 * 33], s[7 * 33]);
;         *(u32x4*)(WT + (size_t)(drow0 + n) * K + k0 + 8 * c) = o; }
;     asm volatile("s_waitcnt lgkmcnt(0)" ::: "memory");
; __global__ void __launch_bounds__(NTHR, 2) fwd_kernel(Args a) {
;     ...
;         for (int it = gw; it < IT_IN; it += NGW) {
;             const int r = it, kb = r / 257, nb = r % 257, n0 = nb * 32; const int d0 = n0 < 3072 ? n0 : (n0 == 3072 ? 8192 : n0 - 32);
;             transpose_item(a.in[I_WIN], DM, INW, WinT, d0, scr, kb * 64, n0, lane);
	ds_write_b32 v16, v64
	s_waitcnt vmcnt(30)
	ds_write_b32 v18, v65
	s_waitcnt vmcnt(29)
	ds_write_b32 v20, v66
	s_waitcnt vmcnt(28)
	ds_write_b32 v22, v67
	s_waitcnt vmcnt(27)
	ds_write_b32 v24, v68
	s_waitcnt vmcnt(26)
	ds_write_b32 v26, v69
	s_waitcnt vmcnt(25)
	ds_write_b32 v28, v70
	s_waitcnt vmcnt(24)
	ds_write_b32 v30, v71
	s_waitcnt vmcnt(23)
	ds_write_b32 v32, v72
	s_waitcnt vmcnt(22)
	ds_write_b32 v34, v73
	s_waitcnt vmcnt(21)
	ds_write_b32 v36, v74
	s_waitcnt vmcnt(20)
	ds_write_b32 v38, v75
	s_waitcnt vmcnt(19)
	ds_write_b32 v40, v76
	s_waitcnt vmcnt(18)
	ds_write_b32 v42, v77
	s_waitcnt vmcnt(17)
	ds_write_b32 v44, v78
	s_waitcnt vmcnt(16)
	ds_write_b32 v46, v79
	v_mad_u64_u32 v[80:81], s[12:13], v113, s5, v[4:5]
	v_mad_u64_u32 v[82:83], s[12:13], v112, s5, v[4:5]
	v_mad_u64_u32 v[84:85], s[12:13], v115, s5, v[4:5]
	v_mad_u64_u32 v[86:87], s[12:13], v114, s5, v[4:5]
	v_mad_u64_u32 v[88:89], s[12:13], v117, s5, v[4:5]
	v_mad_u64_u32 v[90:91], s[12:13], v116, s5, v[4:5]
	v_mad_u64_u32 v[92:93], s[12:13], v119, s5, v[4:5]
	v_mad_u64_u32 v[94:95], s[12:13], v118, s5, v[4:5]
	v_mad_u64_u32 v[96:97], s[12:13], v121, s5, v[4:5]
	v_mad_u64_u32 v[98:99], s[12:13], v120, s5, v[4:5]
	v_mad_u64_u32 v[100:101], s[12:13], v123, s5, v[4:5]
	v_mad_u64_u32 v[102:103], s[12:13], v122, s5, v[4:5]
	v_mad_u64_u32 v[104:105], s[12:13], v125, s5, v[4:5]
	v_mad_u64_u32 v[106:107], s[12:13], v124, s5, v[4:5]
	v_mad_u64_u32 v[108:109], s[12:13], v127, s5, v[4:5]
	v_mad_u64_u32 v[110:111], s[12:13], v126, s5, v[4:5]
	s_waitcnt vmcnt(15)
	ds_write_b32 v80, v128
	s_waitcnt vmcnt(14)
	ds_write_b32 v82, v129
	s_waitcnt vmcnt(13)
	ds_write_b32 v84, v130
	s_waitcnt vmcnt(12)
	ds_write_b32 v86, v131
	s_waitcnt vmcnt(11)
	ds_write_b32 v88, v132
	s_waitcnt vmcnt(10)
	ds_write_b32 v90, v133
	s_waitcnt vmcnt(9)
	ds_write_b32 v92, v134
	s_waitcnt vmcnt(8)
	ds_write_b32 v94, v135
	s_waitcnt vmcnt(7)
	ds_write_b32 v96, v136
	s_waitcnt vmcnt(6)
	ds_write_b32 v98, v137
	s_waitcnt vmcnt(5)
	ds_write_b32 v100, v138
	s_waitcnt vmcnt(4)
	ds_write_b32 v102, v139
	s_waitcnt vmcnt(3)
	ds_write_b32 v104, v140
	s_waitcnt vmcnt(2)
	ds_write_b32 v106, v141
	s_waitcnt vmcnt(1)
	ds_write_b32 v108, v142
	s_waitcnt vmcnt(0)
	ds_write_b32 v110, v143
	s_sub_i32 s3, s2, 32
	s_cmpk_lg_i32 s1, 0x60
	s_waitcnt lgkmcnt(0)
	s_cselect_b32 s3, s3, 0x2000
	s_cmpk_lt_i32 s1, 0x60
	ds_read2_b32 v[8:9], v12 offset0:33 offset1:41
	ds_read2_b32 v[20:21], v12 offset1:8
	ds_read2_b32 v[22:23], v12 offset0:66 offset1:74
	ds_read2_b32 v[24:25], v12 offset0:99 offset1:107
	ds_read2_b32 v[26:27], v12 offset0:132 offset1:140
	ds_read2_b32 v[28:29], v12 offset0:165 offset1:173
	ds_read2_b32 v[30:31], v12 offset0:198 offset1:206
	ds_read2_b32 v[32:33], v12 offset0:231 offset1:239
	s_cselect_b32 s2, s2, s3
	v_or_b32_e32 v36, s2, v11
	s_ashr_i32 s1, s0, 31
	v_ashrrev_i32_e32 v37, 31, v36
	v_lshl_add_u64 v[34:35], s[0:1], 1, v[6:7]
	v_lshlrev_b64 v[36:37], 12, v[36:37]
	s_waitcnt lgkmcnt(6)
	v_cvt_pk_bf16_f32 v16, v20, v8
	s_waitcnt lgkmcnt(4)
	v_cvt_pk_bf16_f32 v17, v22, v24
	s_waitcnt lgkmcnt(2)
	v_cvt_pk_bf16_f32 v18, v26, v28
	s_waitcnt lgkmcnt(0)
	v_cvt_pk_bf16_f32 v19, v30, v32
	v_lshl_add_u64 v[36:37], v[34:35], 0, v[36:37]
	v_or_b32_e32 v8, s2, v13
	global_store_dwordx4 v[36:37], v[16:19], off sc1
	s_add_i32 s4, s4, s70
	s_cmpk_gt_i32 s4, 0x201f
	v_cvt_pk_bf16_f32 v16, v21, v9
	v_ashrrev_i32_e32 v9, 31, v8
	v_cvt_pk_bf16_f32 v17, v23, v25
	v_cvt_pk_bf16_f32 v18, v27, v29
	v_cvt_pk_bf16_f32 v19, v31, v33
	v_lshlrev_b64 v[8:9], 12, v[8:9]
	ds_read2_b32 v[20:21], v12 offset0:49 offset1:57
	ds_read2_b32 v[22:23], v12 offset0:16 offset1:24
	ds_read2_b32 v[24:25], v12 offset0:82 offset1:90
	ds_read2_b32 v[26:27], v12 offset0:115 offset1:123
	ds_read2_b32 v[28:29], v12 offset0:148 offset1:156
	ds_read2_b32 v[30:31], v12 offset0:181 offset1:189
	ds_read2_b32 v[32:33], v12 offset0:214 offset1:222
	ds_read2_b32 v[36:37], v12 offset0:247 offset1:255
	v_lshl_add_u64 v[8:9], v[34:35], 0, v[8:9]
	global_store_dwordx4 v[8:9], v[16:19], off sc1
	v_or_b32_e32 v8, s2, v14
	v_ashrrev_i32_e32 v9, 31, v8
	v_lshlrev_b64 v[8:9], 12, v[8:9]
	s_waitcnt lgkmcnt(6)
	v_cvt_pk_bf16_f32 v16, v22, v20
	s_waitcnt lgkmcnt(4)
	v_cvt_pk_bf16_f32 v17, v24, v26
	s_waitcnt lgkmcnt(2)
	v_cvt_pk_bf16_f32 v18, v28, v30
	s_waitcnt lgkmcnt(0)
	v_cvt_pk_bf16_f32 v19, v32, v36
	v_lshl_add_u64 v[8:9], v[34:35], 0, v[8:9]
	global_store_dwordx4 v[8:9], v[16:19], off sc1
	v_or_b32_e32 v8, s2, v15
	v_ashrrev_i32_e32 v9, 31, v8
	v_lshlrev_b64 v[8:9], 12, v[8:9]
	v_cvt_pk_bf16_f32 v16, v23, v21
	v_cvt_pk_bf16_f32 v17, v25, v27
	v_cvt_pk_bf16_f32 v18, v29, v31
	v_cvt_pk_bf16_f32 v19, v33, v37
	v_lshl_add_u64 v[8:9], v[34:35], 0, v[8:9]
	global_store_dwordx4 v[8:9], v[16:19], off sc1
	s_waitcnt lgkmcnt(0)
	s_cbranch_scc0 .LBB0_21
